# hyena conv2 epilogue: all 16 gate/skip loads hoisted in front of the scattered stores (no load waits behind stores)
# speedup vs baseline: 1.0135x; 1.0135x over previous
.LBB0_1191:
	v_div_scale_f32 v0, s[20:21], v38, v38, 1.0
	s_load_dwordx2 s[20:21], s[14:15], 0x90
	v_rcp_f32_e32 v34, v0
	v_readlane_b32 s2, v255, 52
	s_add_i32 s4, s6, s2
	s_lshl_b64 s[38:39], s[4:5], 2
	v_fma_f32 v35, -v0, v34, 1.0
	s_waitcnt lgkmcnt(0)
	s_add_u32 s20, s20, s38
	v_fmac_f32_e32 v34, v35, v34
	v_div_scale_f32 v35, vcc, 1.0, v38, 1.0
	s_addc_u32 s21, s21, s39
	v_mul_f32_e32 v36, v35, v34
	s_add_u32 s2, s16, s10
	v_fma_f32 v37, -v0, v36, v35
	s_addc_u32 s3, s17, 0
	v_fmac_f32_e32 v36, v37, v34
	s_add_u32 s50, s2, 0xf935800
	v_fma_f32 v0, -v0, v36, v35
	s_addc_u32 s51, s3, 0
	v_div_fmas_f32 v0, v0, v34, v36
	s_and_b64 s[18:19], s[18:19], exec
	v_div_fixup_f32 v38, v0, v38, 1.0
	v_lshlrev_b32_e32 v0, 2, v41
	s_cselect_b32 s2, 11, 8
	v_or3_b32 v34, v0, v43, v42
	v_lshlrev_b32_e32 v0, s2, v40
	v_or_b32_e32 v0, s7, v0
	v_ashrrev_i32_e32 v35, 31, v34
	v_lshl_add_u64 v[40:41], v[0:1], 0, v[34:35]
	v_lshlrev_b64 v[36:37], 1, v[40:41]
	v_lshl_add_u64 v[42:43], s[50:51], 0, v[36:37]
	v_lshl_add_u64 v[36:37], s[46:47], 0, v[36:37]
	global_load_dwordx2 v[44:45], v[36:37], off
	global_load_dword v39, v1, s[20:21] offset:1024
	s_lshl_b32 s2, s6, 1
	global_load_dwordx2 v[140:141], v[36:37], off offset:16
	global_load_dwordx2 v[142:143], v[42:43], off offset:16
	global_load_dwordx2 v[144:145], v[36:37], off offset:32
	global_load_dwordx2 v[146:147], v[42:43], off offset:32
	global_load_dwordx2 v[148:149], v[36:37], off offset:48
	global_load_dwordx2 v[150:151], v[42:43], off offset:48
	global_load_dwordx2 v[152:153], v[36:37], off offset:2048
	global_load_dwordx2 v[154:155], v[42:43], off offset:2048
	global_load_dwordx2 v[156:157], v[36:37], off offset:2064
	global_load_dwordx2 v[158:159], v[42:43], off offset:2064
	global_load_dwordx2 v[160:161], v[36:37], off offset:2080
	global_load_dwordx2 v[162:163], v[42:43], off offset:2080
	global_load_dwordx2 v[164:165], v[36:37], off offset:2096
	global_load_dwordx2 v[166:167], v[42:43], off offset:2096
	global_load_dwordx2 v[42:43], v[42:43], off
	s_add_u32 s2, s16, s2
	s_addc_u32 s3, s17, 0
	s_add_u32 s16, s2, 0x3200000
	s_addc_u32 s17, s3, 0
	s_waitcnt vmcnt(0)
	v_lshlrev_b32_e32 v47, 16, v44
	v_mul_f32_e32 v47, v39, v47
	v_and_b32_e32 v44, 0xffff0000, v44
	v_lshlrev_b32_e32 v35, 16, v42
	v_fmac_f32_e32 v47, v38, v18
	v_lshlrev_b32_e32 v48, 16, v45
	v_mul_f32_e32 v18, v47, v35
	v_mul_f32_e32 v35, v39, v44
	v_fmac_f32_e32 v35, v38, v19
	v_mul_f32_e32 v19, v39, v48
	v_and_b32_e32 v42, 0xffff0000, v42
	v_lshlrev_b32_e32 v46, 16, v43
	v_and_b32_e32 v45, 0xffff0000, v45
	v_fmac_f32_e32 v19, v38, v20
	v_mul_f32_e32 v35, v35, v42
	v_mul_f32_e32 v42, v19, v46
	v_mul_f32_e32 v19, v39, v45
	v_and_b32_e32 v43, 0xffff0000, v43
	v_fmac_f32_e32 v19, v38, v21
	v_mul_f32_e32 v43, v19, v43
	v_bfe_u32 v19, v18, 16, 1
	v_add3_u32 v44, v18, v19, s28
	v_lshlrev_b64 v[18:19], 11, v[40:41]
	v_lshl_add_u64 v[20:21], s[16:17], 0, v[18:19]
	global_store_short_d16_hi v[20:21], v44, off
	v_bfe_u32 v20, v35, 16, 1
	v_add3_u32 v35, v35, v20, s28
	v_or_b32_e32 v20, 0x800, v18
	v_mov_b32_e32 v21, v19
	v_lshl_add_u64 v[20:21], s[16:17], 0, v[20:21]
	global_store_short_d16_hi v[20:21], v35, off
	v_bfe_u32 v20, v42, 16, 1
	v_add3_u32 v35, v42, v20, s28
	v_or_b32_e32 v20, 0x1000, v18
	v_mov_b32_e32 v21, v19
	v_lshl_add_u64 v[20:21], s[16:17], 0, v[20:21]
	global_store_short_d16_hi v[20:21], v35, off
	v_bfe_u32 v20, v43, 16, 1
	v_or_b32_e32 v18, 0x1800, v18
	v_add3_u32 v20, v43, v20, s28
	v_lshl_add_u64 v[18:19], s[16:17], 0, v[18:19]
	global_store_short_d16_hi v[18:19], v20, off
	v_or_b32_e32 v18, 8, v34
	v_ashrrev_i32_e32 v19, 31, v18
	v_lshl_add_u64 v[18:19], v[0:1], 0, v[18:19]
	v_lshl_add_u64 v[20:21], v[18:19], 1, s[50:51]
	v_mov_b32_e32 v20, v142
	v_mov_b32_e32 v21, v143
	s_nop 0
	v_mov_b32_e32 v40, v140
	v_mov_b32_e32 v41, v141
	v_lshlrev_b64 v[18:19], 11, v[18:19]
	v_lshlrev_b32_e32 v35, 16, v20
	v_lshlrev_b32_e32 v43, 16, v40
	v_mul_f32_e32 v43, v39, v43
	v_and_b32_e32 v40, 0xffff0000, v40
	v_fmac_f32_e32 v43, v38, v22
	v_mul_f32_e32 v22, v43, v35
	v_mul_f32_e32 v35, v39, v40
	v_and_b32_e32 v20, 0xffff0000, v20
	v_lshlrev_b32_e32 v44, 16, v41
	v_fmac_f32_e32 v35, v38, v23
	v_mul_f32_e32 v23, v35, v20
	v_mul_f32_e32 v20, v39, v44
	v_lshlrev_b32_e32 v42, 16, v21
	v_and_b32_e32 v41, 0xffff0000, v41
	v_fmac_f32_e32 v20, v38, v24
	v_mul_f32_e32 v24, v20, v42
	v_mul_f32_e32 v20, v39, v41
	v_and_b32_e32 v21, 0xffff0000, v21
	v_fmac_f32_e32 v20, v38, v25
	v_mul_f32_e32 v25, v20, v21
	v_bfe_u32 v20, v22, 16, 1
	v_add3_u32 v22, v22, v20, s28
	v_lshl_add_u64 v[20:21], s[16:17], 0, v[18:19]
	global_store_short_d16_hi v[20:21], v22, off
	v_bfe_u32 v20, v23, 16, 1
	v_add3_u32 v22, v23, v20, s28
	v_or_b32_e32 v20, 0x800, v18
	v_mov_b32_e32 v21, v19
	v_lshl_add_u64 v[20:21], s[16:17], 0, v[20:21]
	global_store_short_d16_hi v[20:21], v22, off
	v_bfe_u32 v20, v24, 16, 1
	v_add3_u32 v22, v24, v20, s28
	v_or_b32_e32 v20, 0x1000, v18
	v_mov_b32_e32 v21, v19
	v_lshl_add_u64 v[20:21], s[16:17], 0, v[20:21]
	global_store_short_d16_hi v[20:21], v22, off
	v_bfe_u32 v20, v25, 16, 1
	v_or_b32_e32 v18, 0x1800, v18
	v_add3_u32 v20, v25, v20, s28
	v_lshl_add_u64 v[18:19], s[16:17], 0, v[18:19]
	global_store_short_d16_hi v[18:19], v20, off
	v_or_b32_e32 v18, 16, v34
	v_ashrrev_i32_e32 v19, 31, v18
	v_lshl_add_u64 v[18:19], v[0:1], 0, v[18:19]
	v_lshl_add_u64 v[20:21], v[18:19], 1, s[50:51]
	v_mov_b32_e32 v20, v146
	v_mov_b32_e32 v21, v147
	s_nop 0
	v_mov_b32_e32 v22, v144
	v_mov_b32_e32 v23, v145
	v_lshlrev_b64 v[18:19], 11, v[18:19]
	v_lshlrev_b32_e32 v24, 16, v20
	v_lshlrev_b32_e32 v35, 16, v22
	v_and_b32_e32 v22, 0xffff0000, v22
	v_mul_f32_e32 v22, v39, v22
	v_and_b32_e32 v20, 0xffff0000, v20
	v_lshlrev_b32_e32 v40, 16, v23
	v_fmac_f32_e32 v22, v38, v27
	v_mul_f32_e32 v22, v22, v20
	v_mul_f32_e32 v20, v39, v40
	v_lshlrev_b32_e32 v25, 16, v21
	v_and_b32_e32 v23, 0xffff0000, v23
	v_mul_f32_e32 v35, v39, v35
	v_fmac_f32_e32 v20, v38, v28
	v_fmac_f32_e32 v35, v38, v26
	v_mul_f32_e32 v25, v20, v25
	v_mul_f32_e32 v20, v39, v23
	v_and_b32_e32 v21, 0xffff0000, v21
	v_mul_f32_e32 v24, v35, v24
	v_fmac_f32_e32 v20, v38, v29
	v_mul_f32_e32 v23, v20, v21
	v_bfe_u32 v20, v24, 16, 1
	v_add3_u32 v24, v24, v20, s28
	v_lshl_add_u64 v[20:21], s[16:17], 0, v[18:19]
	global_store_short_d16_hi v[20:21], v24, off
	v_bfe_u32 v20, v22, 16, 1
	v_add3_u32 v22, v22, v20, s28
	v_or_b32_e32 v20, 0x800, v18
	v_mov_b32_e32 v21, v19
	v_lshl_add_u64 v[20:21], s[16:17], 0, v[20:21]
	global_store_short_d16_hi v[20:21], v22, off
	v_bfe_u32 v20, v25, 16, 1
	v_add3_u32 v22, v25, v20, s28
	v_or_b32_e32 v20, 0x1000, v18
	v_mov_b32_e32 v21, v19
	v_lshl_add_u64 v[20:21], s[16:17], 0, v[20:21]
	global_store_short_d16_hi v[20:21], v22, off
	v_bfe_u32 v20, v23, 16, 1
	v_or_b32_e32 v18, 0x1800, v18
	v_add3_u32 v20, v23, v20, s28
	v_lshl_add_u64 v[18:19], s[16:17], 0, v[18:19]
	global_store_short_d16_hi v[18:19], v20, off
	v_or_b32_e32 v18, 24, v34
	v_ashrrev_i32_e32 v19, 31, v18
	v_lshl_add_u64 v[18:19], v[0:1], 0, v[18:19]
	v_lshl_add_u64 v[20:21], v[18:19], 1, s[50:51]
	v_mov_b32_e32 v20, v150
	v_mov_b32_e32 v21, v151
	s_nop 0
	v_mov_b32_e32 v22, v148
	v_mov_b32_e32 v23, v149
	v_lshlrev_b64 v[18:19], 11, v[18:19]
	v_lshlrev_b32_e32 v24, 16, v20
	v_lshlrev_b32_e32 v26, 16, v22
	v_and_b32_e32 v22, 0xffff0000, v22
	v_mul_f32_e32 v22, v39, v22
	v_and_b32_e32 v20, 0xffff0000, v20
	v_lshlrev_b32_e32 v27, 16, v23
	v_fmac_f32_e32 v22, v38, v31
	v_mul_f32_e32 v22, v22, v20
	v_mul_f32_e32 v20, v39, v27
	v_lshlrev_b32_e32 v25, 16, v21
	v_and_b32_e32 v23, 0xffff0000, v23
	v_mul_f32_e32 v26, v39, v26
	v_fmac_f32_e32 v20, v38, v32
	v_fmac_f32_e32 v26, v38, v30
	v_mul_f32_e32 v25, v20, v25
	v_mul_f32_e32 v20, v39, v23
	v_and_b32_e32 v21, 0xffff0000, v21
	v_mul_f32_e32 v24, v26, v24
	v_fmac_f32_e32 v20, v38, v33
	v_mul_f32_e32 v23, v20, v21
	v_bfe_u32 v20, v24, 16, 1
	v_add3_u32 v24, v24, v20, s28
	v_lshl_add_u64 v[20:21], s[16:17], 0, v[18:19]
	global_store_short_d16_hi v[20:21], v24, off
	v_bfe_u32 v20, v22, 16, 1
	v_add3_u32 v22, v22, v20, s28
	v_or_b32_e32 v20, 0x800, v18
	v_mov_b32_e32 v21, v19
	v_lshl_add_u64 v[20:21], s[16:17], 0, v[20:21]
	global_store_short_d16_hi v[20:21], v22, off
	v_bfe_u32 v20, v25, 16, 1
	v_add3_u32 v22, v25, v20, s28
	v_or_b32_e32 v20, 0x1000, v18
	v_mov_b32_e32 v21, v19
	v_lshl_add_u64 v[20:21], s[16:17], 0, v[20:21]
	global_store_short_d16_hi v[20:21], v22, off
	v_bfe_u32 v20, v23, 16, 1
	v_or_b32_e32 v18, 0x1800, v18
	v_add3_u32 v20, v23, v20, s28
	v_lshl_add_u64 v[18:19], s[16:17], 0, v[18:19]
	global_store_short_d16_hi v[18:19], v20, off
	s_and_b64 exec, exec, s[44:45]
	s_cbranch_execz .LBB0_1156
	v_add_u32_e32 v18, 0x400, v34
	v_ashrrev_i32_e32 v19, 31, v18
	v_lshl_add_u64 v[18:19], v[0:1], 0, v[18:19]
	v_lshlrev_b64 v[20:21], 1, v[18:19]
	v_lshl_add_u64 v[22:23], s[50:51], 0, v[20:21]
	v_lshl_add_u64 v[20:21], s[46:47], 0, v[20:21]
	v_mov_b32_e32 v20, v152
	v_mov_b32_e32 v21, v153
	v_lshlrev_b32_e32 v26, 16, v20
	v_mov_b32_e32 v22, v154
	v_mov_b32_e32 v23, v155
	v_and_b32_e32 v20, 0xffff0000, v20
	v_lshlrev_b32_e32 v27, 16, v21
	v_mul_f32_e32 v20, v39, v20
	v_fmac_f32_e32 v20, v38, v3
	v_mul_f32_e32 v3, v39, v27
	v_and_b32_e32 v21, 0xffff0000, v21
	v_mul_f32_e32 v26, v39, v26
	v_fmac_f32_e32 v3, v38, v4
	v_fmac_f32_e32 v26, v38, v2
	v_lshlrev_b32_e32 v24, 16, v22
	v_and_b32_e32 v22, 0xffff0000, v22
	v_lshlrev_b32_e32 v25, 16, v23
	v_mul_f32_e32 v20, v20, v22
	v_mul_f32_e32 v22, v3, v25
	v_mul_f32_e32 v3, v39, v21
	v_and_b32_e32 v23, 0xffff0000, v23
	v_mul_f32_e32 v2, v26, v24
	v_fmac_f32_e32 v3, v38, v5
	v_mul_f32_e32 v21, v3, v23
	v_bfe_u32 v3, v2, 16, 1
	v_add3_u32 v23, v2, v3, s28
	v_lshlrev_b64 v[2:3], 11, v[18:19]
	v_lshl_add_u64 v[4:5], s[16:17], 0, v[2:3]
	global_store_short_d16_hi v[4:5], v23, off
	v_bfe_u32 v4, v20, 16, 1
	v_add3_u32 v18, v20, v4, s28
	v_or_b32_e32 v4, 0x800, v2
	v_mov_b32_e32 v5, v3
	v_lshl_add_u64 v[4:5], s[16:17], 0, v[4:5]
	global_store_short_d16_hi v[4:5], v18, off
	v_bfe_u32 v4, v22, 16, 1
	v_add3_u32 v18, v22, v4, s28
	v_or_b32_e32 v4, 0x1000, v2
	v_mov_b32_e32 v5, v3
	v_lshl_add_u64 v[4:5], s[16:17], 0, v[4:5]
	global_store_short_d16_hi v[4:5], v18, off
	v_bfe_u32 v4, v21, 16, 1
	v_or_b32_e32 v2, 0x1800, v2
	v_add3_u32 v4, v21, v4, s28
	v_lshl_add_u64 v[2:3], s[16:17], 0, v[2:3]
	global_store_short_d16_hi v[2:3], v4, off
	v_add_u32_e32 v2, 0x408, v34
	v_ashrrev_i32_e32 v3, 31, v2
	v_lshl_add_u64 v[2:3], v[0:1], 0, v[2:3]
	v_lshlrev_b64 v[4:5], 1, v[2:3]
	v_lshl_add_u64 v[18:19], s[50:51], 0, v[4:5]
	v_lshl_add_u64 v[4:5], s[46:47], 0, v[4:5]
	v_mov_b32_e32 v4, v156
	v_mov_b32_e32 v5, v157
	v_lshlrev_b64 v[2:3], 11, v[2:3]
	v_mov_b32_e32 v18, v158
	v_mov_b32_e32 v19, v159
	v_lshlrev_b32_e32 v22, 16, v4
	v_and_b32_e32 v4, 0xffff0000, v4
	v_mul_f32_e32 v4, v39, v4
	v_lshlrev_b32_e32 v20, 16, v18
	v_and_b32_e32 v18, 0xffff0000, v18
	v_lshlrev_b32_e32 v23, 16, v5
	v_fmac_f32_e32 v4, v38, v7
	v_mul_f32_e32 v7, v4, v18
	v_mul_f32_e32 v4, v39, v23
	v_lshlrev_b32_e32 v21, 16, v19
	v_and_b32_e32 v5, 0xffff0000, v5
	v_mul_f32_e32 v22, v39, v22
	v_fmac_f32_e32 v4, v38, v8
	v_fmac_f32_e32 v22, v38, v6
	v_mul_f32_e32 v8, v4, v21
	v_mul_f32_e32 v4, v39, v5
	v_and_b32_e32 v19, 0xffff0000, v19
	v_mul_f32_e32 v6, v22, v20
	v_fmac_f32_e32 v4, v38, v9
	v_mul_f32_e32 v9, v4, v19
	v_bfe_u32 v4, v6, 16, 1
	v_add3_u32 v6, v6, v4, s28
	v_lshl_add_u64 v[4:5], s[16:17], 0, v[2:3]
	global_store_short_d16_hi v[4:5], v6, off
	v_bfe_u32 v4, v7, 16, 1
	v_add3_u32 v6, v7, v4, s28
	v_or_b32_e32 v4, 0x800, v2
	v_mov_b32_e32 v5, v3
	v_lshl_add_u64 v[4:5], s[16:17], 0, v[4:5]
	global_store_short_d16_hi v[4:5], v6, off
	v_bfe_u32 v4, v8, 16, 1
	v_add3_u32 v6, v8, v4, s28
	v_or_b32_e32 v4, 0x1000, v2
	v_mov_b32_e32 v5, v3
	v_lshl_add_u64 v[4:5], s[16:17], 0, v[4:5]
	global_store_short_d16_hi v[4:5], v6, off
	v_bfe_u32 v4, v9, 16, 1
	v_or_b32_e32 v2, 0x1800, v2
	v_add3_u32 v4, v9, v4, s28
	v_lshl_add_u64 v[2:3], s[16:17], 0, v[2:3]
	global_store_short_d16_hi v[2:3], v4, off
	v_add_u32_e32 v2, 0x410, v34
	v_ashrrev_i32_e32 v3, 31, v2
	v_lshl_add_u64 v[2:3], v[0:1], 0, v[2:3]
	v_lshlrev_b64 v[4:5], 1, v[2:3]
	v_lshl_add_u64 v[6:7], s[50:51], 0, v[4:5]
	v_lshl_add_u64 v[4:5], s[46:47], 0, v[4:5]
	v_mov_b32_e32 v4, v160
	v_mov_b32_e32 v5, v161
	v_lshlrev_b64 v[2:3], 11, v[2:3]
	v_mov_b32_e32 v6, v162
	v_mov_b32_e32 v7, v163
	v_lshlrev_b32_e32 v18, 16, v4
	v_and_b32_e32 v4, 0xffff0000, v4
	v_mul_f32_e32 v4, v39, v4
	v_lshlrev_b32_e32 v8, 16, v6
	v_and_b32_e32 v6, 0xffff0000, v6
	v_lshlrev_b32_e32 v19, 16, v5
	v_fmac_f32_e32 v4, v38, v11
	v_mul_f32_e32 v6, v4, v6
	v_mul_f32_e32 v4, v39, v19
	v_lshlrev_b32_e32 v9, 16, v7
	v_and_b32_e32 v5, 0xffff0000, v5
	v_mul_f32_e32 v18, v39, v18
	v_fmac_f32_e32 v4, v38, v12
	v_fmac_f32_e32 v18, v38, v10
	v_mul_f32_e32 v9, v4, v9
	v_mul_f32_e32 v4, v39, v5
	v_and_b32_e32 v7, 0xffff0000, v7
	v_mul_f32_e32 v8, v18, v8
	v_fmac_f32_e32 v4, v38, v13
	v_mul_f32_e32 v7, v4, v7
	v_bfe_u32 v4, v8, 16, 1
	v_add3_u32 v8, v8, v4, s28
	v_lshl_add_u64 v[4:5], s[16:17], 0, v[2:3]
	global_store_short_d16_hi v[4:5], v8, off
	v_bfe_u32 v4, v6, 16, 1
	v_add3_u32 v6, v6, v4, s28
	v_or_b32_e32 v4, 0x800, v2
	v_mov_b32_e32 v5, v3
	v_lshl_add_u64 v[4:5], s[16:17], 0, v[4:5]
	global_store_short_d16_hi v[4:5], v6, off
	v_bfe_u32 v4, v9, 16, 1
	v_add3_u32 v6, v9, v4, s28
	v_or_b32_e32 v4, 0x1000, v2
	v_mov_b32_e32 v5, v3
	v_lshl_add_u64 v[4:5], s[16:17], 0, v[4:5]
	global_store_short_d16_hi v[4:5], v6, off
	v_bfe_u32 v4, v7, 16, 1
	v_or_b32_e32 v2, 0x1800, v2
	v_add3_u32 v4, v7, v4, s28
	v_lshl_add_u64 v[2:3], s[16:17], 0, v[2:3]
	global_store_short_d16_hi v[2:3], v4, off
	v_add_u32_e32 v2, 0x418, v34
	v_ashrrev_i32_e32 v3, 31, v2
	v_lshl_add_u64 v[2:3], v[0:1], 0, v[2:3]
	v_lshlrev_b64 v[4:5], 1, v[2:3]
	v_lshl_add_u64 v[6:7], s[50:51], 0, v[4:5]
	v_lshl_add_u64 v[4:5], s[46:47], 0, v[4:5]
	v_mov_b32_e32 v4, v164
	v_mov_b32_e32 v5, v165
	v_lshlrev_b64 v[2:3], 11, v[2:3]
	v_mov_b32_e32 v6, v166
	v_mov_b32_e32 v7, v167
	v_lshlrev_b32_e32 v9, 16, v4
	v_and_b32_e32 v4, 0xffff0000, v4
	v_mul_f32_e32 v4, v39, v4
	v_lshlrev_b32_e32 v0, 16, v6
	v_and_b32_e32 v6, 0xffff0000, v6
	v_lshlrev_b32_e32 v10, 16, v5
	v_fmac_f32_e32 v4, v38, v15
	v_mul_f32_e32 v6, v4, v6
	v_mul_f32_e32 v4, v39, v10
	v_lshlrev_b32_e32 v8, 16, v7
	v_and_b32_e32 v5, 0xffff0000, v5
	v_mul_f32_e32 v9, v39, v9
	v_fmac_f32_e32 v4, v38, v16
	v_fmac_f32_e32 v9, v38, v14
	v_mul_f32_e32 v8, v4, v8
	v_mul_f32_e32 v4, v39, v5
	v_and_b32_e32 v7, 0xffff0000, v7
	v_mul_f32_e32 v0, v9, v0
	v_fmac_f32_e32 v4, v38, v17
	v_mul_f32_e32 v7, v4, v7
	v_bfe_u32 v4, v0, 16, 1
	v_add3_u32 v0, v0, v4, s28
	v_lshl_add_u64 v[4:5], s[16:17], 0, v[2:3]
	global_store_short_d16_hi v[4:5], v0, off
	v_bfe_u32 v0, v6, 16, 1
	v_or_b32_e32 v4, 0x800, v2
	v_mov_b32_e32 v5, v3
	v_add3_u32 v0, v6, v0, s28
	v_lshl_add_u64 v[4:5], s[16:17], 0, v[4:5]
	global_store_short_d16_hi v[4:5], v0, off
	v_bfe_u32 v0, v8, 16, 1
	v_or_b32_e32 v4, 0x1000, v2
	v_mov_b32_e32 v5, v3
	v_add3_u32 v0, v8, v0, s28
	v_lshl_add_u64 v[4:5], s[16:17], 0, v[4:5]
	global_store_short_d16_hi v[4:5], v0, off
	v_bfe_u32 v0, v7, 16, 1
	v_or_b32_e32 v2, 0x1800, v2
	v_add3_u32 v0, v7, v0, s28
	v_lshl_add_u64 v[2:3], s[16:17], 0, v[2:3]
	global_store_short_d16_hi v[2:3], v0, off
	s_branch .LBB0_1156
